# latency de-serialisation: prep conv pass issues its cb load with the next-token loads (one round trip per token); phase-0 adaLN mat-vec keeps 32 strided weight loads in flight ahead (double-buffered r
# speedup vs baseline: 1.0470x; 1.0100x over previous
.LBB0_77:
	s_or_b64 exec, exec, s[36:37]
	v_mov_b32_e32 v76, v64
	v_mov_b32_e32 v77, v52
	v_mov_b32_e32 v78, v65
	v_mov_b32_e32 v79, v53
	v_mov_b32_e32 v80, v62
	v_mov_b32_e32 v81, v54
	v_mov_b32_e32 v82, v63
	v_mov_b32_e32 v83, v55
	v_mov_b32_e32 v84, v60
	v_mov_b32_e32 v85, v56
	v_mov_b32_e32 v86, v61
	v_mov_b32_e32 v87, v57
	v_mov_b32_e32 v88, v50
	v_mov_b32_e32 v89, v58
	v_mov_b32_e32 v90, v51
	v_mov_b32_e32 v91, v59
	v_pk_mul_f32 v[76:77], v[38:39], v[76:77]
	v_pk_mul_f32 v[78:79], v[4:5], v[78:79]
	v_pk_mul_f32 v[80:81], v[34:35], v[80:81]
	v_pk_mul_f32 v[82:83], v[6:7], v[82:83]
	v_ashrrev_i32_e32 v67, 31, v66
	v_pk_mul_f32 v[84:85], v[32:33], v[84:85]
	v_pk_mul_f32 v[86:87], v[0:1], v[86:87]
	v_pk_mul_f32 v[88:89], v[30:31], v[88:89]
	v_pk_mul_f32 v[90:91], v[2:3], v[90:91]
	v_fma_f32 v71, v8, v40, v76
	v_fma_f32 v76, v9, v41, v78
	v_fma_f32 v78, v10, v42, v80
	v_fma_f32 v80, v11, v43, v82
	v_lshlrev_b64 v[66:67], 11, v[66:67]
	v_fma_f32 v82, v16, v44, v84
	v_fma_f32 v84, v17, v45, v86
	v_fma_f32 v86, v18, v46, v88
	v_fma_f32 v88, v19, v47, v90
	v_mov_b64_e32 v[42:43], v[62:63]
	v_mov_b64_e32 v[44:45], v[60:61]
	v_add_f32_e32 v60, v71, v77
	v_add_f32_e32 v61, v76, v79
	v_add_f32_e32 v62, v78, v81
	v_add_f32_e32 v63, v80, v83
	v_lshl_add_u64 v[46:47], v[26:27], 0, v[66:67]
	v_mov_b64_e32 v[40:41], v[64:65]
	v_add_f32_e32 v64, v82, v85
	v_add_f32_e32 v65, v84, v87
	v_add_f32_e32 v66, v86, v89
	v_add_f32_e32 v67, v88, v91
	v_add_f32_e32 v60, v12, v60
	v_add_f32_e32 v61, v13, v61
	v_add_f32_e32 v62, v14, v62
	v_add_f32_e32 v63, v15, v63
	s_add_i32 s7, s7, 1
	v_add_f32_e32 v64, v20, v64
	v_add_f32_e32 v65, v21, v65
	v_add_f32_e32 v66, v22, v66
	v_add_f32_e32 v67, v23, v67
	s_cmp_eq_u32 s7, 16
	s_waitcnt vmcnt(0)
	v_lshlrev_b32_e32 v71, 16, v92
	v_and_b32_e32 v72, 0xffff0000, v92
	v_lshlrev_b32_e32 v76, 16, v93
	v_and_b32_e32 v73, 0xffff0000, v93
	v_lshlrev_b32_e32 v77, 16, v94
	v_and_b32_e32 v74, 0xffff0000, v94
	v_lshlrev_b32_e32 v78, 16, v95
	v_and_b32_e32 v75, 0xffff0000, v95
	v_mul_f32_e32 v60, v60, v71
	v_mul_f32_e32 v61, v61, v72
	v_mul_f32_e32 v62, v62, v76
	v_mul_f32_e32 v63, v63, v73
	v_mul_f32_e32 v64, v64, v77
	v_mul_f32_e32 v65, v65, v74
	v_mul_f32_e32 v66, v66, v78
	v_mul_f32_e32 v67, v67, v75
	v_cvt_pk_bf16_f32 v60, v60, v61
	v_cvt_pk_bf16_f32 v61, v62, v63
	v_cvt_pk_bf16_f32 v62, v64, v65
	v_cvt_pk_bf16_f32 v63, v66, v67
	global_store_dwordx4 v[46:47], v[60:63], off
	v_mov_b64_e32 v[46:47], v[50:51]
	s_cbranch_scc1 .LBB0_73
.LBB0_78:
	v_mov_b64_e32 v[64:65], v[52:53]
	v_add_u32_e32 v52, s7, v49
	v_mov_b32_e32 v181, v180
	v_mov_b64_e32 v[50:51], v[58:59]
	v_mov_b64_e32 v[60:61], v[56:57]
	v_mov_b64_e32 v[62:63], v[54:55]
	v_add_u32_e32 v66, s7, v29
	v_mad_i64_i32 v[96:97], s[8:9], v66, s26, v[24:25]
	global_load_dwordx4 v[92:95], v[96:97], off
	v_cmp_gt_u32_e32 vcc, s3, v52
	v_mov_b64_e32 v[52:53], v[180:181]
	v_mov_b64_e32 v[54:55], v[180:181]
	v_mov_b64_e32 v[56:57], v[180:181]
	v_mov_b64_e32 v[58:59], v[180:181]
	s_and_saveexec_b64 s[36:37], vcc
	s_cbranch_execz .LBB0_77
	v_add_u32_e32 v52, 1, v66
	v_mad_i64_i32 v[56:57], s[8:9], v52, s26, v[24:25]
	global_load_dwordx4 v[52:55], v[56:57], off offset:1024
	s_nop 0
	global_load_dwordx4 v[56:59], v[56:57], off offset:2048
	s_waitcnt vmcnt(1)
	v_lshlrev_b32_e32 v72, 16, v52
	v_and_b32_e32 v73, 0xffff0000, v52
	s_waitcnt vmcnt(0)
	v_lshlrev_b32_e32 v74, 16, v56
	v_and_b32_e32 v75, 0xffff0000, v56
	v_lshlrev_b32_e32 v76, 16, v53
	v_and_b32_e32 v77, 0xffff0000, v53
	v_lshlrev_b32_e32 v56, 16, v57
	v_and_b32_e32 v57, 0xffff0000, v57
	v_lshlrev_b32_e32 v78, 16, v54
	v_and_b32_e32 v79, 0xffff0000, v54
	v_lshlrev_b32_e32 v80, 16, v58
	v_and_b32_e32 v81, 0xffff0000, v58
	v_lshlrev_b32_e32 v82, 16, v55
	v_and_b32_e32 v83, 0xffff0000, v55
	v_lshlrev_b32_e32 v58, 16, v59
	v_and_b32_e32 v59, 0xffff0000, v59
	v_pk_mul_f32 v[52:53], v[72:73], v[74:75]
	v_pk_mul_f32 v[54:55], v[76:77], v[56:57]
	v_pk_mul_f32 v[56:57], v[78:79], v[80:81]
	v_pk_mul_f32 v[58:59], v[82:83], v[58:59]
	s_branch .LBB0_77

.LBB0_241:
	s_or_b64 exec, exec, s[28:29]
	v_mad_i64_i32 v[16:17], s[6:7], v10, v8, 0
	v_lshl_add_u64 v[2:3], v[16:17], 2, v[2:3]
	v_ashrrev_i32_e32 v1, 31, v0
	v_lshl_add_u64 v[16:17], v[0:1], 2, v[2:3]
	v_mov_b32_e32 v0, 0
	v_lshlrev_b32_e32 v18, 5, v10
	v_mov_b32_e32 v19, v180
	v_lshlrev_b32_e32 v20, 2, v10
	v_mov_b32_e32 v21, v180
	s_mov_b32 s5, 0
	v_mov_b32_e32 v1, v0
	v_mov_b32_e32 v2, v0
	v_mov_b32_e32 v3, v0
	v_mov_b32_e32 v140, v16
	v_mov_b32_e32 v141, v17
	global_load_dword v76, v[140:141], off
	v_lshl_add_u64 v[140:141], v[140:141], 0, v[20:21]
	global_load_dword v77, v[140:141], off
	v_lshl_add_u64 v[140:141], v[140:141], 0, v[20:21]
	global_load_dword v78, v[140:141], off
	v_lshl_add_u64 v[140:141], v[140:141], 0, v[20:21]
	global_load_dword v79, v[140:141], off
	v_lshl_add_u64 v[140:141], v[140:141], 0, v[20:21]
	global_load_dword v80, v[140:141], off
	v_lshl_add_u64 v[140:141], v[140:141], 0, v[20:21]
	global_load_dword v81, v[140:141], off
	v_lshl_add_u64 v[140:141], v[140:141], 0, v[20:21]
	global_load_dword v82, v[140:141], off
	v_lshl_add_u64 v[140:141], v[140:141], 0, v[20:21]
	global_load_dword v83, v[140:141], off
	v_lshl_add_u64 v[140:141], v[140:141], 0, v[20:21]
	global_load_dword v84, v[140:141], off
	v_lshl_add_u64 v[140:141], v[140:141], 0, v[20:21]
	global_load_dword v85, v[140:141], off
	v_lshl_add_u64 v[140:141], v[140:141], 0, v[20:21]
	global_load_dword v86, v[140:141], off
	v_lshl_add_u64 v[140:141], v[140:141], 0, v[20:21]
	global_load_dword v87, v[140:141], off
	v_lshl_add_u64 v[140:141], v[140:141], 0, v[20:21]
	global_load_dword v88, v[140:141], off
	v_lshl_add_u64 v[140:141], v[140:141], 0, v[20:21]
	global_load_dword v89, v[140:141], off
	v_lshl_add_u64 v[140:141], v[140:141], 0, v[20:21]
	global_load_dword v90, v[140:141], off
	v_lshl_add_u64 v[140:141], v[140:141], 0, v[20:21]
	global_load_dword v91, v[140:141], off
	v_lshl_add_u64 v[140:141], v[140:141], 0, v[20:21]
	global_load_dword v92, v[140:141], off
	v_lshl_add_u64 v[140:141], v[140:141], 0, v[20:21]
	global_load_dword v93, v[140:141], off
	v_lshl_add_u64 v[140:141], v[140:141], 0, v[20:21]
	global_load_dword v94, v[140:141], off
	v_lshl_add_u64 v[140:141], v[140:141], 0, v[20:21]
	global_load_dword v95, v[140:141], off
	v_lshl_add_u64 v[140:141], v[140:141], 0, v[20:21]
	global_load_dword v96, v[140:141], off
	v_lshl_add_u64 v[140:141], v[140:141], 0, v[20:21]
	global_load_dword v97, v[140:141], off
	v_lshl_add_u64 v[140:141], v[140:141], 0, v[20:21]
	global_load_dword v98, v[140:141], off
	v_lshl_add_u64 v[140:141], v[140:141], 0, v[20:21]
	global_load_dword v99, v[140:141], off
	v_lshl_add_u64 v[140:141], v[140:141], 0, v[20:21]
	global_load_dword v100, v[140:141], off
	v_lshl_add_u64 v[140:141], v[140:141], 0, v[20:21]
	global_load_dword v101, v[140:141], off
	v_lshl_add_u64 v[140:141], v[140:141], 0, v[20:21]
	global_load_dword v102, v[140:141], off
	v_lshl_add_u64 v[140:141], v[140:141], 0, v[20:21]
	global_load_dword v103, v[140:141], off
	v_lshl_add_u64 v[140:141], v[140:141], 0, v[20:21]
	global_load_dword v104, v[140:141], off
	v_lshl_add_u64 v[140:141], v[140:141], 0, v[20:21]
	global_load_dword v105, v[140:141], off
	v_lshl_add_u64 v[140:141], v[140:141], 0, v[20:21]
	global_load_dword v106, v[140:141], off
	v_lshl_add_u64 v[140:141], v[140:141], 0, v[20:21]
	global_load_dword v107, v[140:141], off
	v_lshl_add_u64 v[140:141], v[140:141], 0, v[20:21]
	global_load_dword v108, v[140:141], off
	v_lshl_add_u64 v[140:141], v[140:141], 0, v[20:21]
	global_load_dword v109, v[140:141], off
	v_lshl_add_u64 v[140:141], v[140:141], 0, v[20:21]
	global_load_dword v110, v[140:141], off
	v_lshl_add_u64 v[140:141], v[140:141], 0, v[20:21]
	global_load_dword v111, v[140:141], off
	v_lshl_add_u64 v[140:141], v[140:141], 0, v[20:21]
	global_load_dword v112, v[140:141], off
	v_lshl_add_u64 v[140:141], v[140:141], 0, v[20:21]
	global_load_dword v113, v[140:141], off
	v_lshl_add_u64 v[140:141], v[140:141], 0, v[20:21]
	global_load_dword v114, v[140:141], off
	v_lshl_add_u64 v[140:141], v[140:141], 0, v[20:21]
	global_load_dword v115, v[140:141], off
	v_lshl_add_u64 v[140:141], v[140:141], 0, v[20:21]
	global_load_dword v116, v[140:141], off
	v_lshl_add_u64 v[140:141], v[140:141], 0, v[20:21]
	global_load_dword v117, v[140:141], off
	v_lshl_add_u64 v[140:141], v[140:141], 0, v[20:21]
	global_load_dword v118, v[140:141], off
	v_lshl_add_u64 v[140:141], v[140:141], 0, v[20:21]
	global_load_dword v119, v[140:141], off
	v_lshl_add_u64 v[140:141], v[140:141], 0, v[20:21]
	global_load_dword v120, v[140:141], off
	v_lshl_add_u64 v[140:141], v[140:141], 0, v[20:21]
	global_load_dword v121, v[140:141], off
	v_lshl_add_u64 v[140:141], v[140:141], 0, v[20:21]
	global_load_dword v122, v[140:141], off
	v_lshl_add_u64 v[140:141], v[140:141], 0, v[20:21]
	global_load_dword v123, v[140:141], off
	v_lshl_add_u64 v[140:141], v[140:141], 0, v[20:21]
	global_load_dword v124, v[140:141], off
	v_lshl_add_u64 v[140:141], v[140:141], 0, v[20:21]
	global_load_dword v125, v[140:141], off
	v_lshl_add_u64 v[140:141], v[140:141], 0, v[20:21]
	global_load_dword v126, v[140:141], off
	v_lshl_add_u64 v[140:141], v[140:141], 0, v[20:21]
	global_load_dword v127, v[140:141], off
	v_lshl_add_u64 v[140:141], v[140:141], 0, v[20:21]
	global_load_dword v128, v[140:141], off
	v_lshl_add_u64 v[140:141], v[140:141], 0, v[20:21]
	global_load_dword v129, v[140:141], off
	v_lshl_add_u64 v[140:141], v[140:141], 0, v[20:21]
	global_load_dword v130, v[140:141], off
	v_lshl_add_u64 v[140:141], v[140:141], 0, v[20:21]
	global_load_dword v131, v[140:141], off
	v_lshl_add_u64 v[140:141], v[140:141], 0, v[20:21]
	global_load_dword v132, v[140:141], off
	v_lshl_add_u64 v[140:141], v[140:141], 0, v[20:21]
	global_load_dword v133, v[140:141], off
	v_lshl_add_u64 v[140:141], v[140:141], 0, v[20:21]
	global_load_dword v134, v[140:141], off
	v_lshl_add_u64 v[140:141], v[140:141], 0, v[20:21]
	global_load_dword v135, v[140:141], off
	v_lshl_add_u64 v[140:141], v[140:141], 0, v[20:21]
	global_load_dword v136, v[140:141], off
	v_lshl_add_u64 v[140:141], v[140:141], 0, v[20:21]
	global_load_dword v137, v[140:141], off
	v_lshl_add_u64 v[140:141], v[140:141], 0, v[20:21]
	global_load_dword v138, v[140:141], off
	v_lshl_add_u64 v[140:141], v[140:141], 0, v[20:21]
	global_load_dword v139, v[140:141], off
	v_lshl_add_u64 v[140:141], v[140:141], 0, v[20:21]
	ds_read_b128 v[24:27], v5 offset:0
	ds_read_b128 v[28:31], v5 offset:16
	ds_read_b128 v[32:35], v5 offset:4096
	ds_read_b128 v[36:39], v5 offset:4112
	ds_read_b128 v[40:43], v5 offset:8192
	ds_read_b128 v[44:47], v5 offset:8208
	ds_read_b128 v[48:51], v5 offset:12288
	ds_read_b128 v[52:55], v5 offset:12304
	s_waitcnt lgkmcnt(0)
	v_mov_b32_e32 v72, v24
	v_mov_b32_e32 v73, v32
	v_mov_b32_e32 v74, v40
	v_mov_b32_e32 v75, v48
	v_mov_b32_e32 v32, v25
	v_mov_b32_e32 v48, v41
	v_mov_b32_e32 v24, v26
	v_mov_b32_e32 v25, v34
	v_mov_b32_e32 v40, v42
	v_mov_b32_e32 v41, v50
	v_mov_b32_e32 v34, v27
	v_mov_b32_e32 v50, v43
	v_mov_b32_e32 v26, v28
	v_mov_b32_e32 v27, v36
	v_mov_b32_e32 v42, v44
	v_mov_b32_e32 v43, v52
	v_mov_b32_e32 v36, v29
	v_mov_b32_e32 v52, v45
	v_mov_b32_e32 v28, v30
	v_mov_b32_e32 v29, v38
	v_mov_b32_e32 v44, v46
	v_mov_b32_e32 v45, v54
	v_mov_b32_e32 v38, v31
	v_mov_b32_e32 v54, v47
	s_waitcnt vmcnt(63)
	v_pk_fma_f32 v[0:1], v[76:77], v[72:73], v[0:1] op_sel_hi:[0,1,1]
	v_pk_fma_f32 v[2:3], v[76:77], v[74:75], v[2:3] op_sel_hi:[0,1,1]
	s_waitcnt vmcnt(62)
	v_pk_fma_f32 v[0:1], v[76:77], v[32:33], v[0:1] op_sel:[1,0,0]
	v_pk_fma_f32 v[2:3], v[76:77], v[48:49], v[2:3] op_sel:[1,0,0]
	s_waitcnt vmcnt(61)
	v_pk_fma_f32 v[0:1], v[78:79], v[24:25], v[0:1] op_sel_hi:[0,1,1]
	v_pk_fma_f32 v[2:3], v[78:79], v[40:41], v[2:3] op_sel_hi:[0,1,1]
	s_waitcnt vmcnt(60)
	v_pk_fma_f32 v[0:1], v[78:79], v[34:35], v[0:1] op_sel:[1,0,0]
	v_pk_fma_f32 v[2:3], v[78:79], v[50:51], v[2:3] op_sel:[1,0,0]
	s_waitcnt vmcnt(59)
	v_pk_fma_f32 v[0:1], v[80:81], v[26:27], v[0:1] op_sel_hi:[0,1,1]
	v_pk_fma_f32 v[2:3], v[80:81], v[42:43], v[2:3] op_sel_hi:[0,1,1]
	s_waitcnt vmcnt(58)
	v_pk_fma_f32 v[0:1], v[80:81], v[36:37], v[0:1] op_sel:[1,0,0]
	v_pk_fma_f32 v[2:3], v[80:81], v[52:53], v[2:3] op_sel:[1,0,0]
	s_waitcnt vmcnt(57)
	v_pk_fma_f32 v[0:1], v[82:83], v[28:29], v[0:1] op_sel_hi:[0,1,1]
	v_pk_fma_f32 v[2:3], v[82:83], v[44:45], v[2:3] op_sel_hi:[0,1,1]
	s_waitcnt vmcnt(56)
	v_pk_fma_f32 v[0:1], v[82:83], v[38:39], v[0:1] op_sel:[1,0,0]
	v_pk_fma_f32 v[2:3], v[82:83], v[54:55], v[2:3] op_sel:[1,0,0]
	ds_read_b128 v[24:27], v5 offset:32
	ds_read_b128 v[28:31], v5 offset:48
	ds_read_b128 v[32:35], v5 offset:4128
	ds_read_b128 v[36:39], v5 offset:4144
	ds_read_b128 v[40:43], v5 offset:8224
	ds_read_b128 v[44:47], v5 offset:8240
	ds_read_b128 v[48:51], v5 offset:12320
	ds_read_b128 v[52:55], v5 offset:12336
	s_waitcnt lgkmcnt(0)
	v_mov_b32_e32 v72, v24
	v_mov_b32_e32 v73, v32
	v_mov_b32_e32 v74, v40
	v_mov_b32_e32 v75, v48
	v_mov_b32_e32 v32, v25
	v_mov_b32_e32 v48, v41
	v_mov_b32_e32 v24, v26
	v_mov_b32_e32 v25, v34
	v_mov_b32_e32 v40, v42
	v_mov_b32_e32 v41, v50
	v_mov_b32_e32 v34, v27
	v_mov_b32_e32 v50, v43
	v_mov_b32_e32 v26, v28
	v_mov_b32_e32 v27, v36
	v_mov_b32_e32 v42, v44
	v_mov_b32_e32 v43, v52
	v_mov_b32_e32 v36, v29
	v_mov_b32_e32 v52, v45
	v_mov_b32_e32 v28, v30
	v_mov_b32_e32 v29, v38
	v_mov_b32_e32 v44, v46
	v_mov_b32_e32 v45, v54
	v_mov_b32_e32 v38, v31
	v_mov_b32_e32 v54, v47
	s_waitcnt vmcnt(55)
	v_pk_fma_f32 v[0:1], v[84:85], v[72:73], v[0:1] op_sel_hi:[0,1,1]
	v_pk_fma_f32 v[2:3], v[84:85], v[74:75], v[2:3] op_sel_hi:[0,1,1]
	s_waitcnt vmcnt(54)
	v_pk_fma_f32 v[0:1], v[84:85], v[32:33], v[0:1] op_sel:[1,0,0]
	v_pk_fma_f32 v[2:3], v[84:85], v[48:49], v[2:3] op_sel:[1,0,0]
	s_waitcnt vmcnt(53)
	v_pk_fma_f32 v[0:1], v[86:87], v[24:25], v[0:1] op_sel_hi:[0,1,1]
	v_pk_fma_f32 v[2:3], v[86:87], v[40:41], v[2:3] op_sel_hi:[0,1,1]
	s_waitcnt vmcnt(52)
	v_pk_fma_f32 v[0:1], v[86:87], v[34:35], v[0:1] op_sel:[1,0,0]
	v_pk_fma_f32 v[2:3], v[86:87], v[50:51], v[2:3] op_sel:[1,0,0]
	s_waitcnt vmcnt(51)
	v_pk_fma_f32 v[0:1], v[88:89], v[26:27], v[0:1] op_sel_hi:[0,1,1]
	v_pk_fma_f32 v[2:3], v[88:89], v[42:43], v[2:3] op_sel_hi:[0,1,1]
	s_waitcnt vmcnt(50)
	v_pk_fma_f32 v[0:1], v[88:89], v[36:37], v[0:1] op_sel:[1,0,0]
	v_pk_fma_f32 v[2:3], v[88:89], v[52:53], v[2:3] op_sel:[1,0,0]
	s_waitcnt vmcnt(49)
	v_pk_fma_f32 v[0:1], v[90:91], v[28:29], v[0:1] op_sel_hi:[0,1,1]
	v_pk_fma_f32 v[2:3], v[90:91], v[44:45], v[2:3] op_sel_hi:[0,1,1]
	s_waitcnt vmcnt(48)
	v_pk_fma_f32 v[0:1], v[90:91], v[38:39], v[0:1] op_sel:[1,0,0]
	v_pk_fma_f32 v[2:3], v[90:91], v[54:55], v[2:3] op_sel:[1,0,0]
	ds_read_b128 v[24:27], v5 offset:64
	ds_read_b128 v[28:31], v5 offset:80
	ds_read_b128 v[32:35], v5 offset:4160
	ds_read_b128 v[36:39], v5 offset:4176
	ds_read_b128 v[40:43], v5 offset:8256
	ds_read_b128 v[44:47], v5 offset:8272
	ds_read_b128 v[48:51], v5 offset:12352
	ds_read_b128 v[52:55], v5 offset:12368
	s_waitcnt lgkmcnt(0)
	v_mov_b32_e32 v72, v24
	v_mov_b32_e32 v73, v32
	v_mov_b32_e32 v74, v40
	v_mov_b32_e32 v75, v48
	v_mov_b32_e32 v32, v25
	v_mov_b32_e32 v48, v41
	v_mov_b32_e32 v24, v26
	v_mov_b32_e32 v25, v34
	v_mov_b32_e32 v40, v42
	v_mov_b32_e32 v41, v50
	v_mov_b32_e32 v34, v27
	v_mov_b32_e32 v50, v43
	v_mov_b32_e32 v26, v28
	v_mov_b32_e32 v27, v36
	v_mov_b32_e32 v42, v44
	v_mov_b32_e32 v43, v52
	v_mov_b32_e32 v36, v29
	v_mov_b32_e32 v52, v45
	v_mov_b32_e32 v28, v30
	v_mov_b32_e32 v29, v38
	v_mov_b32_e32 v44, v46
	v_mov_b32_e32 v45, v54
	v_mov_b32_e32 v38, v31
	v_mov_b32_e32 v54, v47
	s_waitcnt vmcnt(47)
	v_pk_fma_f32 v[0:1], v[92:93], v[72:73], v[0:1] op_sel_hi:[0,1,1]
	v_pk_fma_f32 v[2:3], v[92:93], v[74:75], v[2:3] op_sel_hi:[0,1,1]
	s_waitcnt vmcnt(46)
	v_pk_fma_f32 v[0:1], v[92:93], v[32:33], v[0:1] op_sel:[1,0,0]
	v_pk_fma_f32 v[2:3], v[92:93], v[48:49], v[2:3] op_sel:[1,0,0]
	s_waitcnt vmcnt(45)
	v_pk_fma_f32 v[0:1], v[94:95], v[24:25], v[0:1] op_sel_hi:[0,1,1]
	v_pk_fma_f32 v[2:3], v[94:95], v[40:41], v[2:3] op_sel_hi:[0,1,1]
	s_waitcnt vmcnt(44)
	v_pk_fma_f32 v[0:1], v[94:95], v[34:35], v[0:1] op_sel:[1,0,0]
	v_pk_fma_f32 v[2:3], v[94:95], v[50:51], v[2:3] op_sel:[1,0,0]
	s_waitcnt vmcnt(43)
	v_pk_fma_f32 v[0:1], v[96:97], v[26:27], v[0:1] op_sel_hi:[0,1,1]
	v_pk_fma_f32 v[2:3], v[96:97], v[42:43], v[2:3] op_sel_hi:[0,1,1]
	s_waitcnt vmcnt(42)
	v_pk_fma_f32 v[0:1], v[96:97], v[36:37], v[0:1] op_sel:[1,0,0]
	v_pk_fma_f32 v[2:3], v[96:97], v[52:53], v[2:3] op_sel:[1,0,0]
	s_waitcnt vmcnt(41)
	v_pk_fma_f32 v[0:1], v[98:99], v[28:29], v[0:1] op_sel_hi:[0,1,1]
	v_pk_fma_f32 v[2:3], v[98:99], v[44:45], v[2:3] op_sel_hi:[0,1,1]
	s_waitcnt vmcnt(40)
	v_pk_fma_f32 v[0:1], v[98:99], v[38:39], v[0:1] op_sel:[1,0,0]
	v_pk_fma_f32 v[2:3], v[98:99], v[54:55], v[2:3] op_sel:[1,0,0]
	ds_read_b128 v[24:27], v5 offset:96
	ds_read_b128 v[28:31], v5 offset:112
	ds_read_b128 v[32:35], v5 offset:4192
	ds_read_b128 v[36:39], v5 offset:4208
	ds_read_b128 v[40:43], v5 offset:8288
	ds_read_b128 v[44:47], v5 offset:8304
	ds_read_b128 v[48:51], v5 offset:12384
	ds_read_b128 v[52:55], v5 offset:12400
	s_waitcnt lgkmcnt(0)
	v_mov_b32_e32 v72, v24
	v_mov_b32_e32 v73, v32
	v_mov_b32_e32 v74, v40
	v_mov_b32_e32 v75, v48
	v_mov_b32_e32 v32, v25
	v_mov_b32_e32 v48, v41
	v_mov_b32_e32 v24, v26
	v_mov_b32_e32 v25, v34
	v_mov_b32_e32 v40, v42
	v_mov_b32_e32 v41, v50
	v_mov_b32_e32 v34, v27
	v_mov_b32_e32 v50, v43
	v_mov_b32_e32 v26, v28
	v_mov_b32_e32 v27, v36
	v_mov_b32_e32 v42, v44
	v_mov_b32_e32 v43, v52
	v_mov_b32_e32 v36, v29
	v_mov_b32_e32 v52, v45
	v_mov_b32_e32 v28, v30
	v_mov_b32_e32 v29, v38
	v_mov_b32_e32 v44, v46
	v_mov_b32_e32 v45, v54
	v_mov_b32_e32 v38, v31
	v_mov_b32_e32 v54, v47
	s_waitcnt vmcnt(39)
	v_pk_fma_f32 v[0:1], v[100:101], v[72:73], v[0:1] op_sel_hi:[0,1,1]
	v_pk_fma_f32 v[2:3], v[100:101], v[74:75], v[2:3] op_sel_hi:[0,1,1]
	s_waitcnt vmcnt(38)
	v_pk_fma_f32 v[0:1], v[100:101], v[32:33], v[0:1] op_sel:[1,0,0]
	v_pk_fma_f32 v[2:3], v[100:101], v[48:49], v[2:3] op_sel:[1,0,0]
	s_waitcnt vmcnt(37)
	v_pk_fma_f32 v[0:1], v[102:103], v[24:25], v[0:1] op_sel_hi:[0,1,1]
	v_pk_fma_f32 v[2:3], v[102:103], v[40:41], v[2:3] op_sel_hi:[0,1,1]
	s_waitcnt vmcnt(36)
	v_pk_fma_f32 v[0:1], v[102:103], v[34:35], v[0:1] op_sel:[1,0,0]
	v_pk_fma_f32 v[2:3], v[102:103], v[50:51], v[2:3] op_sel:[1,0,0]
	s_waitcnt vmcnt(35)
	v_pk_fma_f32 v[0:1], v[104:105], v[26:27], v[0:1] op_sel_hi:[0,1,1]
	v_pk_fma_f32 v[2:3], v[104:105], v[42:43], v[2:3] op_sel_hi:[0,1,1]
	s_waitcnt vmcnt(34)
	v_pk_fma_f32 v[0:1], v[104:105], v[36:37], v[0:1] op_sel:[1,0,0]
	v_pk_fma_f32 v[2:3], v[104:105], v[52:53], v[2:3] op_sel:[1,0,0]
	s_waitcnt vmcnt(33)
	v_pk_fma_f32 v[0:1], v[106:107], v[28:29], v[0:1] op_sel_hi:[0,1,1]
	v_pk_fma_f32 v[2:3], v[106:107], v[44:45], v[2:3] op_sel_hi:[0,1,1]
	s_waitcnt vmcnt(32)
	v_pk_fma_f32 v[0:1], v[106:107], v[38:39], v[0:1] op_sel:[1,0,0]
	v_pk_fma_f32 v[2:3], v[106:107], v[54:55], v[2:3] op_sel:[1,0,0]
	global_load_dword v76, v[140:141], off
	v_lshl_add_u64 v[140:141], v[140:141], 0, v[20:21]
	global_load_dword v77, v[140:141], off
	v_lshl_add_u64 v[140:141], v[140:141], 0, v[20:21]
	global_load_dword v78, v[140:141], off
	v_lshl_add_u64 v[140:141], v[140:141], 0, v[20:21]
	global_load_dword v79, v[140:141], off
	v_lshl_add_u64 v[140:141], v[140:141], 0, v[20:21]
	global_load_dword v80, v[140:141], off
	v_lshl_add_u64 v[140:141], v[140:141], 0, v[20:21]
	global_load_dword v81, v[140:141], off
	v_lshl_add_u64 v[140:141], v[140:141], 0, v[20:21]
	global_load_dword v82, v[140:141], off
	v_lshl_add_u64 v[140:141], v[140:141], 0, v[20:21]
	global_load_dword v83, v[140:141], off
	v_lshl_add_u64 v[140:141], v[140:141], 0, v[20:21]
	global_load_dword v84, v[140:141], off
	v_lshl_add_u64 v[140:141], v[140:141], 0, v[20:21]
	global_load_dword v85, v[140:141], off
	v_lshl_add_u64 v[140:141], v[140:141], 0, v[20:21]
	global_load_dword v86, v[140:141], off
	v_lshl_add_u64 v[140:141], v[140:141], 0, v[20:21]
	global_load_dword v87, v[140:141], off
	v_lshl_add_u64 v[140:141], v[140:141], 0, v[20:21]
	global_load_dword v88, v[140:141], off
	v_lshl_add_u64 v[140:141], v[140:141], 0, v[20:21]
	global_load_dword v89, v[140:141], off
	v_lshl_add_u64 v[140:141], v[140:141], 0, v[20:21]
	global_load_dword v90, v[140:141], off
	v_lshl_add_u64 v[140:141], v[140:141], 0, v[20:21]
	global_load_dword v91, v[140:141], off
	v_lshl_add_u64 v[140:141], v[140:141], 0, v[20:21]
	global_load_dword v92, v[140:141], off
	v_lshl_add_u64 v[140:141], v[140:141], 0, v[20:21]
	global_load_dword v93, v[140:141], off
	v_lshl_add_u64 v[140:141], v[140:141], 0, v[20:21]
	global_load_dword v94, v[140:141], off
	v_lshl_add_u64 v[140:141], v[140:141], 0, v[20:21]
	global_load_dword v95, v[140:141], off
	v_lshl_add_u64 v[140:141], v[140:141], 0, v[20:21]
	global_load_dword v96, v[140:141], off
	v_lshl_add_u64 v[140:141], v[140:141], 0, v[20:21]
	global_load_dword v97, v[140:141], off
	v_lshl_add_u64 v[140:141], v[140:141], 0, v[20:21]
	global_load_dword v98, v[140:141], off
	v_lshl_add_u64 v[140:141], v[140:141], 0, v[20:21]
	global_load_dword v99, v[140:141], off
	v_lshl_add_u64 v[140:141], v[140:141], 0, v[20:21]
	global_load_dword v100, v[140:141], off
	v_lshl_add_u64 v[140:141], v[140:141], 0, v[20:21]
	global_load_dword v101, v[140:141], off
	v_lshl_add_u64 v[140:141], v[140:141], 0, v[20:21]
	global_load_dword v102, v[140:141], off
	v_lshl_add_u64 v[140:141], v[140:141], 0, v[20:21]
	global_load_dword v103, v[140:141], off
	v_lshl_add_u64 v[140:141], v[140:141], 0, v[20:21]
	global_load_dword v104, v[140:141], off
	v_lshl_add_u64 v[140:141], v[140:141], 0, v[20:21]
	global_load_dword v105, v[140:141], off
	v_lshl_add_u64 v[140:141], v[140:141], 0, v[20:21]
	global_load_dword v106, v[140:141], off
	v_lshl_add_u64 v[140:141], v[140:141], 0, v[20:21]
	global_load_dword v107, v[140:141], off
	v_lshl_add_u64 v[140:141], v[140:141], 0, v[20:21]
	ds_read_b128 v[24:27], v5 offset:128
	ds_read_b128 v[28:31], v5 offset:144
	ds_read_b128 v[32:35], v5 offset:4224
	ds_read_b128 v[36:39], v5 offset:4240
	ds_read_b128 v[40:43], v5 offset:8320
	ds_read_b128 v[44:47], v5 offset:8336
	ds_read_b128 v[48:51], v5 offset:12416
	ds_read_b128 v[52:55], v5 offset:12432
	s_waitcnt lgkmcnt(0)
	v_mov_b32_e32 v72, v24
	v_mov_b32_e32 v73, v32
	v_mov_b32_e32 v74, v40
	v_mov_b32_e32 v75, v48
	v_mov_b32_e32 v32, v25
	v_mov_b32_e32 v48, v41
	v_mov_b32_e32 v24, v26
	v_mov_b32_e32 v25, v34
	v_mov_b32_e32 v40, v42
	v_mov_b32_e32 v41, v50
	v_mov_b32_e32 v34, v27
	v_mov_b32_e32 v50, v43
	v_mov_b32_e32 v26, v28
	v_mov_b32_e32 v27, v36
	v_mov_b32_e32 v42, v44
	v_mov_b32_e32 v43, v52
	v_mov_b32_e32 v36, v29
	v_mov_b32_e32 v52, v45
	v_mov_b32_e32 v28, v30
	v_mov_b32_e32 v29, v38
	v_mov_b32_e32 v44, v46
	v_mov_b32_e32 v45, v54
	v_mov_b32_e32 v38, v31
	v_mov_b32_e32 v54, v47
	s_waitcnt vmcnt(63)
	v_pk_fma_f32 v[0:1], v[108:109], v[72:73], v[0:1] op_sel_hi:[0,1,1]
	v_pk_fma_f32 v[2:3], v[108:109], v[74:75], v[2:3] op_sel_hi:[0,1,1]
	s_waitcnt vmcnt(62)
	v_pk_fma_f32 v[0:1], v[108:109], v[32:33], v[0:1] op_sel:[1,0,0]
	v_pk_fma_f32 v[2:3], v[108:109], v[48:49], v[2:3] op_sel:[1,0,0]
	s_waitcnt vmcnt(61)
	v_pk_fma_f32 v[0:1], v[110:111], v[24:25], v[0:1] op_sel_hi:[0,1,1]
	v_pk_fma_f32 v[2:3], v[110:111], v[40:41], v[2:3] op_sel_hi:[0,1,1]
	s_waitcnt vmcnt(60)
	v_pk_fma_f32 v[0:1], v[110:111], v[34:35], v[0:1] op_sel:[1,0,0]
	v_pk_fma_f32 v[2:3], v[110:111], v[50:51], v[2:3] op_sel:[1,0,0]
	s_waitcnt vmcnt(59)
	v_pk_fma_f32 v[0:1], v[112:113], v[26:27], v[0:1] op_sel_hi:[0,1,1]
	v_pk_fma_f32 v[2:3], v[112:113], v[42:43], v[2:3] op_sel_hi:[0,1,1]
	s_waitcnt vmcnt(58)
	v_pk_fma_f32 v[0:1], v[112:113], v[36:37], v[0:1] op_sel:[1,0,0]
	v_pk_fma_f32 v[2:3], v[112:113], v[52:53], v[2:3] op_sel:[1,0,0]
	s_waitcnt vmcnt(57)
	v_pk_fma_f32 v[0:1], v[114:115], v[28:29], v[0:1] op_sel_hi:[0,1,1]
	v_pk_fma_f32 v[2:3], v[114:115], v[44:45], v[2:3] op_sel_hi:[0,1,1]
	s_waitcnt vmcnt(56)
	v_pk_fma_f32 v[0:1], v[114:115], v[38:39], v[0:1] op_sel:[1,0,0]
	v_pk_fma_f32 v[2:3], v[114:115], v[54:55], v[2:3] op_sel:[1,0,0]
	ds_read_b128 v[24:27], v5 offset:160
	ds_read_b128 v[28:31], v5 offset:176
	ds_read_b128 v[32:35], v5 offset:4256
	ds_read_b128 v[36:39], v5 offset:4272
	ds_read_b128 v[40:43], v5 offset:8352
	ds_read_b128 v[44:47], v5 offset:8368
	ds_read_b128 v[48:51], v5 offset:12448
	ds_read_b128 v[52:55], v5 offset:12464
	s_waitcnt lgkmcnt(0)
	v_mov_b32_e32 v72, v24
	v_mov_b32_e32 v73, v32
	v_mov_b32_e32 v74, v40
	v_mov_b32_e32 v75, v48
	v_mov_b32_e32 v32, v25
	v_mov_b32_e32 v48, v41
	v_mov_b32_e32 v24, v26
	v_mov_b32_e32 v25, v34
	v_mov_b32_e32 v40, v42
	v_mov_b32_e32 v41, v50
	v_mov_b32_e32 v34, v27
	v_mov_b32_e32 v50, v43
	v_mov_b32_e32 v26, v28
	v_mov_b32_e32 v27, v36
	v_mov_b32_e32 v42, v44
	v_mov_b32_e32 v43, v52
	v_mov_b32_e32 v36, v29
	v_mov_b32_e32 v52, v45
	v_mov_b32_e32 v28, v30
	v_mov_b32_e32 v29, v38
	v_mov_b32_e32 v44, v46
	v_mov_b32_e32 v45, v54
	v_mov_b32_e32 v38, v31
	v_mov_b32_e32 v54, v47
	s_waitcnt vmcnt(55)
	v_pk_fma_f32 v[0:1], v[116:117], v[72:73], v[0:1] op_sel_hi:[0,1,1]
	v_pk_fma_f32 v[2:3], v[116:117], v[74:75], v[2:3] op_sel_hi:[0,1,1]
	s_waitcnt vmcnt(54)
	v_pk_fma_f32 v[0:1], v[116:117], v[32:33], v[0:1] op_sel:[1,0,0]
	v_pk_fma_f32 v[2:3], v[116:117], v[48:49], v[2:3] op_sel:[1,0,0]
	s_waitcnt vmcnt(53)
	v_pk_fma_f32 v[0:1], v[118:119], v[24:25], v[0:1] op_sel_hi:[0,1,1]
	v_pk_fma_f32 v[2:3], v[118:119], v[40:41], v[2:3] op_sel_hi:[0,1,1]
	s_waitcnt vmcnt(52)
	v_pk_fma_f32 v[0:1], v[118:119], v[34:35], v[0:1] op_sel:[1,0,0]
	v_pk_fma_f32 v[2:3], v[118:119], v[50:51], v[2:3] op_sel:[1,0,0]
	s_waitcnt vmcnt(51)
	v_pk_fma_f32 v[0:1], v[120:121], v[26:27], v[0:1] op_sel_hi:[0,1,1]
	v_pk_fma_f32 v[2:3], v[120:121], v[42:43], v[2:3] op_sel_hi:[0,1,1]
	s_waitcnt vmcnt(50)
	v_pk_fma_f32 v[0:1], v[120:121], v[36:37], v[0:1] op_sel:[1,0,0]
	v_pk_fma_f32 v[2:3], v[120:121], v[52:53], v[2:3] op_sel:[1,0,0]
	s_waitcnt vmcnt(49)
	v_pk_fma_f32 v[0:1], v[122:123], v[28:29], v[0:1] op_sel_hi:[0,1,1]
	v_pk_fma_f32 v[2:3], v[122:123], v[44:45], v[2:3] op_sel_hi:[0,1,1]
	s_waitcnt vmcnt(48)
	v_pk_fma_f32 v[0:1], v[122:123], v[38:39], v[0:1] op_sel:[1,0,0]
	v_pk_fma_f32 v[2:3], v[122:123], v[54:55], v[2:3] op_sel:[1,0,0]
	ds_read_b128 v[24:27], v5 offset:192
	ds_read_b128 v[28:31], v5 offset:208
	ds_read_b128 v[32:35], v5 offset:4288
	ds_read_b128 v[36:39], v5 offset:4304
	ds_read_b128 v[40:43], v5 offset:8384
	ds_read_b128 v[44:47], v5 offset:8400
	ds_read_b128 v[48:51], v5 offset:12480
	ds_read_b128 v[52:55], v5 offset:12496
	s_waitcnt lgkmcnt(0)
	v_mov_b32_e32 v72, v24
	v_mov_b32_e32 v73, v32
	v_mov_b32_e32 v74, v40
	v_mov_b32_e32 v75, v48
	v_mov_b32_e32 v32, v25
	v_mov_b32_e32 v48, v41
	v_mov_b32_e32 v24, v26
	v_mov_b32_e32 v25, v34
	v_mov_b32_e32 v40, v42
	v_mov_b32_e32 v41, v50
	v_mov_b32_e32 v34, v27
	v_mov_b32_e32 v50, v43
	v_mov_b32_e32 v26, v28
	v_mov_b32_e32 v27, v36
	v_mov_b32_e32 v42, v44
	v_mov_b32_e32 v43, v52
	v_mov_b32_e32 v36, v29
	v_mov_b32_e32 v52, v45
	v_mov_b32_e32 v28, v30
	v_mov_b32_e32 v29, v38
	v_mov_b32_e32 v44, v46
	v_mov_b32_e32 v45, v54
	v_mov_b32_e32 v38, v31
	v_mov_b32_e32 v54, v47
	s_waitcnt vmcnt(47)
	v_pk_fma_f32 v[0:1], v[124:125], v[72:73], v[0:1] op_sel_hi:[0,1,1]
	v_pk_fma_f32 v[2:3], v[124:125], v[74:75], v[2:3] op_sel_hi:[0,1,1]
	s_waitcnt vmcnt(46)
	v_pk_fma_f32 v[0:1], v[124:125], v[32:33], v[0:1] op_sel:[1,0,0]
	v_pk_fma_f32 v[2:3], v[124:125], v[48:49], v[2:3] op_sel:[1,0,0]
	s_waitcnt vmcnt(45)
	v_pk_fma_f32 v[0:1], v[126:127], v[24:25], v[0:1] op_sel_hi:[0,1,1]
	v_pk_fma_f32 v[2:3], v[126:127], v[40:41], v[2:3] op_sel_hi:[0,1,1]
	s_waitcnt vmcnt(44)
	v_pk_fma_f32 v[0:1], v[126:127], v[34:35], v[0:1] op_sel:[1,0,0]
	v_pk_fma_f32 v[2:3], v[126:127], v[50:51], v[2:3] op_sel:[1,0,0]
	s_waitcnt vmcnt(43)
	v_pk_fma_f32 v[0:1], v[128:129], v[26:27], v[0:1] op_sel_hi:[0,1,1]
	v_pk_fma_f32 v[2:3], v[128:129], v[42:43], v[2:3] op_sel_hi:[0,1,1]
	s_waitcnt vmcnt(42)
	v_pk_fma_f32 v[0:1], v[128:129], v[36:37], v[0:1] op_sel:[1,0,0]
	v_pk_fma_f32 v[2:3], v[128:129], v[52:53], v[2:3] op_sel:[1,0,0]
	s_waitcnt vmcnt(41)
	v_pk_fma_f32 v[0:1], v[130:131], v[28:29], v[0:1] op_sel_hi:[0,1,1]
	v_pk_fma_f32 v[2:3], v[130:131], v[44:45], v[2:3] op_sel_hi:[0,1,1]
	s_waitcnt vmcnt(40)
	v_pk_fma_f32 v[0:1], v[130:131], v[38:39], v[0:1] op_sel:[1,0,0]
	v_pk_fma_f32 v[2:3], v[130:131], v[54:55], v[2:3] op_sel:[1,0,0]
	ds_read_b128 v[24:27], v5 offset:224
	ds_read_b128 v[28:31], v5 offset:240
	ds_read_b128 v[32:35], v5 offset:4320
	ds_read_b128 v[36:39], v5 offset:4336
	ds_read_b128 v[40:43], v5 offset:8416
	ds_read_b128 v[44:47], v5 offset:8432
	ds_read_b128 v[48:51], v5 offset:12512
	ds_read_b128 v[52:55], v5 offset:12528
	s_waitcnt lgkmcnt(0)
	v_mov_b32_e32 v72, v24
	v_mov_b32_e32 v73, v32
	v_mov_b32_e32 v74, v40
	v_mov_b32_e32 v75, v48
	v_mov_b32_e32 v32, v25
	v_mov_b32_e32 v48, v41
	v_mov_b32_e32 v24, v26
	v_mov_b32_e32 v25, v34
	v_mov_b32_e32 v40, v42
	v_mov_b32_e32 v41, v50
	v_mov_b32_e32 v34, v27
	v_mov_b32_e32 v50, v43
	v_mov_b32_e32 v26, v28
	v_mov_b32_e32 v27, v36
	v_mov_b32_e32 v42, v44
	v_mov_b32_e32 v43, v52
	v_mov_b32_e32 v36, v29
	v_mov_b32_e32 v52, v45
	v_mov_b32_e32 v28, v30
	v_mov_b32_e32 v29, v38
	v_mov_b32_e32 v44, v46
	v_mov_b32_e32 v45, v54
	v_mov_b32_e32 v38, v31
	v_mov_b32_e32 v54, v47
	s_waitcnt vmcnt(39)
	v_pk_fma_f32 v[0:1], v[132:133], v[72:73], v[0:1] op_sel_hi:[0,1,1]
	v_pk_fma_f32 v[2:3], v[132:133], v[74:75], v[2:3] op_sel_hi:[0,1,1]
	s_waitcnt vmcnt(38)
	v_pk_fma_f32 v[0:1], v[132:133], v[32:33], v[0:1] op_sel:[1,0,0]
	v_pk_fma_f32 v[2:3], v[132:133], v[48:49], v[2:3] op_sel:[1,0,0]
	s_waitcnt vmcnt(37)
	v_pk_fma_f32 v[0:1], v[134:135], v[24:25], v[0:1] op_sel_hi:[0,1,1]
	v_pk_fma_f32 v[2:3], v[134:135], v[40:41], v[2:3] op_sel_hi:[0,1,1]
	s_waitcnt vmcnt(36)
	v_pk_fma_f32 v[0:1], v[134:135], v[34:35], v[0:1] op_sel:[1,0,0]
	v_pk_fma_f32 v[2:3], v[134:135], v[50:51], v[2:3] op_sel:[1,0,0]
	s_waitcnt vmcnt(35)
	v_pk_fma_f32 v[0:1], v[136:137], v[26:27], v[0:1] op_sel_hi:[0,1,1]
	v_pk_fma_f32 v[2:3], v[136:137], v[42:43], v[2:3] op_sel_hi:[0,1,1]
	s_waitcnt vmcnt(34)
	v_pk_fma_f32 v[0:1], v[136:137], v[36:37], v[0:1] op_sel:[1,0,0]
	v_pk_fma_f32 v[2:3], v[136:137], v[52:53], v[2:3] op_sel:[1,0,0]
	s_waitcnt vmcnt(33)
	v_pk_fma_f32 v[0:1], v[138:139], v[28:29], v[0:1] op_sel_hi:[0,1,1]
	v_pk_fma_f32 v[2:3], v[138:139], v[44:45], v[2:3] op_sel_hi:[0,1,1]
	s_waitcnt vmcnt(32)
	v_pk_fma_f32 v[0:1], v[138:139], v[38:39], v[0:1] op_sel:[1,0,0]
	v_pk_fma_f32 v[2:3], v[138:139], v[54:55], v[2:3] op_sel:[1,0,0]
	global_load_dword v108, v[140:141], off
	v_lshl_add_u64 v[140:141], v[140:141], 0, v[20:21]
	global_load_dword v109, v[140:141], off
	v_lshl_add_u64 v[140:141], v[140:141], 0, v[20:21]
	global_load_dword v110, v[140:141], off
	v_lshl_add_u64 v[140:141], v[140:141], 0, v[20:21]
	global_load_dword v111, v[140:141], off
	v_lshl_add_u64 v[140:141], v[140:141], 0, v[20:21]
	global_load_dword v112, v[140:141], off
	v_lshl_add_u64 v[140:141], v[140:141], 0, v[20:21]
	global_load_dword v113, v[140:141], off
	v_lshl_add_u64 v[140:141], v[140:141], 0, v[20:21]
	global_load_dword v114, v[140:141], off
	v_lshl_add_u64 v[140:141], v[140:141], 0, v[20:21]
	global_load_dword v115, v[140:141], off
	v_lshl_add_u64 v[140:141], v[140:141], 0, v[20:21]
	global_load_dword v116, v[140:141], off
	v_lshl_add_u64 v[140:141], v[140:141], 0, v[20:21]
	global_load_dword v117, v[140:141], off
	v_lshl_add_u64 v[140:141], v[140:141], 0, v[20:21]
	global_load_dword v118, v[140:141], off
	v_lshl_add_u64 v[140:141], v[140:141], 0, v[20:21]
	global_load_dword v119, v[140:141], off
	v_lshl_add_u64 v[140:141], v[140:141], 0, v[20:21]
	global_load_dword v120, v[140:141], off
	v_lshl_add_u64 v[140:141], v[140:141], 0, v[20:21]
	global_load_dword v121, v[140:141], off
	v_lshl_add_u64 v[140:141], v[140:141], 0, v[20:21]
	global_load_dword v122, v[140:141], off
	v_lshl_add_u64 v[140:141], v[140:141], 0, v[20:21]
	global_load_dword v123, v[140:141], off
	v_lshl_add_u64 v[140:141], v[140:141], 0, v[20:21]
	global_load_dword v124, v[140:141], off
	v_lshl_add_u64 v[140:141], v[140:141], 0, v[20:21]
	global_load_dword v125, v[140:141], off
	v_lshl_add_u64 v[140:141], v[140:141], 0, v[20:21]
	global_load_dword v126, v[140:141], off
	v_lshl_add_u64 v[140:141], v[140:141], 0, v[20:21]
	global_load_dword v127, v[140:141], off
	v_lshl_add_u64 v[140:141], v[140:141], 0, v[20:21]
	global_load_dword v128, v[140:141], off
	v_lshl_add_u64 v[140:141], v[140:141], 0, v[20:21]
	global_load_dword v129, v[140:141], off
	v_lshl_add_u64 v[140:141], v[140:141], 0, v[20:21]
	global_load_dword v130, v[140:141], off
	v_lshl_add_u64 v[140:141], v[140:141], 0, v[20:21]
	global_load_dword v131, v[140:141], off
	v_lshl_add_u64 v[140:141], v[140:141], 0, v[20:21]
	global_load_dword v132, v[140:141], off
	v_lshl_add_u64 v[140:141], v[140:141], 0, v[20:21]
	global_load_dword v133, v[140:141], off
	v_lshl_add_u64 v[140:141], v[140:141], 0, v[20:21]
	global_load_dword v134, v[140:141], off
	v_lshl_add_u64 v[140:141], v[140:141], 0, v[20:21]
	global_load_dword v135, v[140:141], off
	v_lshl_add_u64 v[140:141], v[140:141], 0, v[20:21]
	global_load_dword v136, v[140:141], off
	v_lshl_add_u64 v[140:141], v[140:141], 0, v[20:21]
	global_load_dword v137, v[140:141], off
	v_lshl_add_u64 v[140:141], v[140:141], 0, v[20:21]
	global_load_dword v138, v[140:141], off
	v_lshl_add_u64 v[140:141], v[140:141], 0, v[20:21]
	global_load_dword v139, v[140:141], off
	v_lshl_add_u64 v[140:141], v[140:141], 0, v[20:21]
	ds_read_b128 v[24:27], v5 offset:256
	ds_read_b128 v[28:31], v5 offset:272
	ds_read_b128 v[32:35], v5 offset:4352
	ds_read_b128 v[36:39], v5 offset:4368
	ds_read_b128 v[40:43], v5 offset:8448
	ds_read_b128 v[44:47], v5 offset:8464
	ds_read_b128 v[48:51], v5 offset:12544
	ds_read_b128 v[52:55], v5 offset:12560
	s_waitcnt lgkmcnt(0)
	v_mov_b32_e32 v72, v24
	v_mov_b32_e32 v73, v32
	v_mov_b32_e32 v74, v40
	v_mov_b32_e32 v75, v48
	v_mov_b32_e32 v32, v25
	v_mov_b32_e32 v48, v41
	v_mov_b32_e32 v24, v26
	v_mov_b32_e32 v25, v34
	v_mov_b32_e32 v40, v42
	v_mov_b32_e32 v41, v50
	v_mov_b32_e32 v34, v27
	v_mov_b32_e32 v50, v43
	v_mov_b32_e32 v26, v28
	v_mov_b32_e32 v27, v36
	v_mov_b32_e32 v42, v44
	v_mov_b32_e32 v43, v52
	v_mov_b32_e32 v36, v29
	v_mov_b32_e32 v52, v45
	v_mov_b32_e32 v28, v30
	v_mov_b32_e32 v29, v38
	v_mov_b32_e32 v44, v46
	v_mov_b32_e32 v45, v54
	v_mov_b32_e32 v38, v31
	v_mov_b32_e32 v54, v47
	s_waitcnt vmcnt(63)
	v_pk_fma_f32 v[0:1], v[76:77], v[72:73], v[0:1] op_sel_hi:[0,1,1]
	v_pk_fma_f32 v[2:3], v[76:77], v[74:75], v[2:3] op_sel_hi:[0,1,1]
	s_waitcnt vmcnt(62)
	v_pk_fma_f32 v[0:1], v[76:77], v[32:33], v[0:1] op_sel:[1,0,0]
	v_pk_fma_f32 v[2:3], v[76:77], v[48:49], v[2:3] op_sel:[1,0,0]
	s_waitcnt vmcnt(61)
	v_pk_fma_f32 v[0:1], v[78:79], v[24:25], v[0:1] op_sel_hi:[0,1,1]
	v_pk_fma_f32 v[2:3], v[78:79], v[40:41], v[2:3] op_sel_hi:[0,1,1]
	s_waitcnt vmcnt(60)
	v_pk_fma_f32 v[0:1], v[78:79], v[34:35], v[0:1] op_sel:[1,0,0]
	v_pk_fma_f32 v[2:3], v[78:79], v[50:51], v[2:3] op_sel:[1,0,0]
	s_waitcnt vmcnt(59)
	v_pk_fma_f32 v[0:1], v[80:81], v[26:27], v[0:1] op_sel_hi:[0,1,1]
	v_pk_fma_f32 v[2:3], v[80:81], v[42:43], v[2:3] op_sel_hi:[0,1,1]
	s_waitcnt vmcnt(58)
	v_pk_fma_f32 v[0:1], v[80:81], v[36:37], v[0:1] op_sel:[1,0,0]
	v_pk_fma_f32 v[2:3], v[80:81], v[52:53], v[2:3] op_sel:[1,0,0]
	s_waitcnt vmcnt(57)
	v_pk_fma_f32 v[0:1], v[82:83], v[28:29], v[0:1] op_sel_hi:[0,1,1]
	v_pk_fma_f32 v[2:3], v[82:83], v[44:45], v[2:3] op_sel_hi:[0,1,1]
	s_waitcnt vmcnt(56)
	v_pk_fma_f32 v[0:1], v[82:83], v[38:39], v[0:1] op_sel:[1,0,0]
	v_pk_fma_f32 v[2:3], v[82:83], v[54:55], v[2:3] op_sel:[1,0,0]
	ds_read_b128 v[24:27], v5 offset:288
	ds_read_b128 v[28:31], v5 offset:304
	ds_read_b128 v[32:35], v5 offset:4384
	ds_read_b128 v[36:39], v5 offset:4400
	ds_read_b128 v[40:43], v5 offset:8480
	ds_read_b128 v[44:47], v5 offset:8496
	ds_read_b128 v[48:51], v5 offset:12576
	ds_read_b128 v[52:55], v5 offset:12592
	s_waitcnt lgkmcnt(0)
	v_mov_b32_e32 v72, v24
	v_mov_b32_e32 v73, v32
	v_mov_b32_e32 v74, v40
	v_mov_b32_e32 v75, v48
	v_mov_b32_e32 v32, v25
	v_mov_b32_e32 v48, v41
	v_mov_b32_e32 v24, v26
	v_mov_b32_e32 v25, v34
	v_mov_b32_e32 v40, v42
	v_mov_b32_e32 v41, v50
	v_mov_b32_e32 v34, v27
	v_mov_b32_e32 v50, v43
	v_mov_b32_e32 v26, v28
	v_mov_b32_e32 v27, v36
	v_mov_b32_e32 v42, v44
	v_mov_b32_e32 v43, v52
	v_mov_b32_e32 v36, v29
	v_mov_b32_e32 v52, v45
	v_mov_b32_e32 v28, v30
	v_mov_b32_e32 v29, v38
	v_mov_b32_e32 v44, v46
	v_mov_b32_e32 v45, v54
	v_mov_b32_e32 v38, v31
	v_mov_b32_e32 v54, v47
	s_waitcnt vmcnt(55)
	v_pk_fma_f32 v[0:1], v[84:85], v[72:73], v[0:1] op_sel_hi:[0,1,1]
	v_pk_fma_f32 v[2:3], v[84:85], v[74:75], v[2:3] op_sel_hi:[0,1,1]
	s_waitcnt vmcnt(54)
	v_pk_fma_f32 v[0:1], v[84:85], v[32:33], v[0:1] op_sel:[1,0,0]
	v_pk_fma_f32 v[2:3], v[84:85], v[48:49], v[2:3] op_sel:[1,0,0]
	s_waitcnt vmcnt(53)
	v_pk_fma_f32 v[0:1], v[86:87], v[24:25], v[0:1] op_sel_hi:[0,1,1]
	v_pk_fma_f32 v[2:3], v[86:87], v[40:41], v[2:3] op_sel_hi:[0,1,1]
	s_waitcnt vmcnt(52)
	v_pk_fma_f32 v[0:1], v[86:87], v[34:35], v[0:1] op_sel:[1,0,0]
	v_pk_fma_f32 v[2:3], v[86:87], v[50:51], v[2:3] op_sel:[1,0,0]
	s_waitcnt vmcnt(51)
	v_pk_fma_f32 v[0:1], v[88:89], v[26:27], v[0:1] op_sel_hi:[0,1,1]
	v_pk_fma_f32 v[2:3], v[88:89], v[42:43], v[2:3] op_sel_hi:[0,1,1]
	s_waitcnt vmcnt(50)
	v_pk_fma_f32 v[0:1], v[88:89], v[36:37], v[0:1] op_sel:[1,0,0]
	v_pk_fma_f32 v[2:3], v[88:89], v[52:53], v[2:3] op_sel:[1,0,0]
	s_waitcnt vmcnt(49)
	v_pk_fma_f32 v[0:1], v[90:91], v[28:29], v[0:1] op_sel_hi:[0,1,1]
	v_pk_fma_f32 v[2:3], v[90:91], v[44:45], v[2:3] op_sel_hi:[0,1,1]
	s_waitcnt vmcnt(48)
	v_pk_fma_f32 v[0:1], v[90:91], v[38:39], v[0:1] op_sel:[1,0,0]
	v_pk_fma_f32 v[2:3], v[90:91], v[54:55], v[2:3] op_sel:[1,0,0]
	ds_read_b128 v[24:27], v5 offset:320
	ds_read_b128 v[28:31], v5 offset:336
	ds_read_b128 v[32:35], v5 offset:4416
	ds_read_b128 v[36:39], v5 offset:4432
	ds_read_b128 v[40:43], v5 offset:8512
	ds_read_b128 v[44:47], v5 offset:8528
	ds_read_b128 v[48:51], v5 offset:12608
	ds_read_b128 v[52:55], v5 offset:12624
	s_waitcnt lgkmcnt(0)
	v_mov_b32_e32 v72, v24
	v_mov_b32_e32 v73, v32
	v_mov_b32_e32 v74, v40
	v_mov_b32_e32 v75, v48
	v_mov_b32_e32 v32, v25
	v_mov_b32_e32 v48, v41
	v_mov_b32_e32 v24, v26
	v_mov_b32_e32 v25, v34
	v_mov_b32_e32 v40, v42
	v_mov_b32_e32 v41, v50
	v_mov_b32_e32 v34, v27
	v_mov_b32_e32 v50, v43
	v_mov_b32_e32 v26, v28
	v_mov_b32_e32 v27, v36
	v_mov_b32_e32 v42, v44
	v_mov_b32_e32 v43, v52
	v_mov_b32_e32 v36, v29
	v_mov_b32_e32 v52, v45
	v_mov_b32_e32 v28, v30
	v_mov_b32_e32 v29, v38
	v_mov_b32_e32 v44, v46
	v_mov_b32_e32 v45, v54
	v_mov_b32_e32 v38, v31
	v_mov_b32_e32 v54, v47
	s_waitcnt vmcnt(47)
	v_pk_fma_f32 v[0:1], v[92:93], v[72:73], v[0:1] op_sel_hi:[0,1,1]
	v_pk_fma_f32 v[2:3], v[92:93], v[74:75], v[2:3] op_sel_hi:[0,1,1]
	s_waitcnt vmcnt(46)
	v_pk_fma_f32 v[0:1], v[92:93], v[32:33], v[0:1] op_sel:[1,0,0]
	v_pk_fma_f32 v[2:3], v[92:93], v[48:49], v[2:3] op_sel:[1,0,0]
	s_waitcnt vmcnt(45)
	v_pk_fma_f32 v[0:1], v[94:95], v[24:25], v[0:1] op_sel_hi:[0,1,1]
	v_pk_fma_f32 v[2:3], v[94:95], v[40:41], v[2:3] op_sel_hi:[0,1,1]
	s_waitcnt vmcnt(44)
	v_pk_fma_f32 v[0:1], v[94:95], v[34:35], v[0:1] op_sel:[1,0,0]
	v_pk_fma_f32 v[2:3], v[94:95], v[50:51], v[2:3] op_sel:[1,0,0]
	s_waitcnt vmcnt(43)
	v_pk_fma_f32 v[0:1], v[96:97], v[26:27], v[0:1] op_sel_hi:[0,1,1]
	v_pk_fma_f32 v[2:3], v[96:97], v[42:43], v[2:3] op_sel_hi:[0,1,1]
	s_waitcnt vmcnt(42)
	v_pk_fma_f32 v[0:1], v[96:97], v[36:37], v[0:1] op_sel:[1,0,0]
	v_pk_fma_f32 v[2:3], v[96:97], v[52:53], v[2:3] op_sel:[1,0,0]
	s_waitcnt vmcnt(41)
	v_pk_fma_f32 v[0:1], v[98:99], v[28:29], v[0:1] op_sel_hi:[0,1,1]
	v_pk_fma_f32 v[2:3], v[98:99], v[44:45], v[2:3] op_sel_hi:[0,1,1]
	s_waitcnt vmcnt(40)
	v_pk_fma_f32 v[0:1], v[98:99], v[38:39], v[0:1] op_sel:[1,0,0]
	v_pk_fma_f32 v[2:3], v[98:99], v[54:55], v[2:3] op_sel:[1,0,0]
	ds_read_b128 v[24:27], v5 offset:352
	ds_read_b128 v[28:31], v5 offset:368
	ds_read_b128 v[32:35], v5 offset:4448
	ds_read_b128 v[36:39], v5 offset:4464
	ds_read_b128 v[40:43], v5 offset:8544
	ds_read_b128 v[44:47], v5 offset:8560
	ds_read_b128 v[48:51], v5 offset:12640
	ds_read_b128 v[52:55], v5 offset:12656
	s_waitcnt lgkmcnt(0)
	v_mov_b32_e32 v72, v24
	v_mov_b32_e32 v73, v32
	v_mov_b32_e32 v74, v40
	v_mov_b32_e32 v75, v48
	v_mov_b32_e32 v32, v25
	v_mov_b32_e32 v48, v41
	v_mov_b32_e32 v24, v26
	v_mov_b32_e32 v25, v34
	v_mov_b32_e32 v40, v42
	v_mov_b32_e32 v41, v50
	v_mov_b32_e32 v34, v27
	v_mov_b32_e32 v50, v43
	v_mov_b32_e32 v26, v28
	v_mov_b32_e32 v27, v36
	v_mov_b32_e32 v42, v44
	v_mov_b32_e32 v43, v52
	v_mov_b32_e32 v36, v29
	v_mov_b32_e32 v52, v45
	v_mov_b32_e32 v28, v30
	v_mov_b32_e32 v29, v38
	v_mov_b32_e32 v44, v46
	v_mov_b32_e32 v45, v54
	v_mov_b32_e32 v38, v31
	v_mov_b32_e32 v54, v47
	s_waitcnt vmcnt(39)
	v_pk_fma_f32 v[0:1], v[100:101], v[72:73], v[0:1] op_sel_hi:[0,1,1]
	v_pk_fma_f32 v[2:3], v[100:101], v[74:75], v[2:3] op_sel_hi:[0,1,1]
	s_waitcnt vmcnt(38)
	v_pk_fma_f32 v[0:1], v[100:101], v[32:33], v[0:1] op_sel:[1,0,0]
	v_pk_fma_f32 v[2:3], v[100:101], v[48:49], v[2:3] op_sel:[1,0,0]
	s_waitcnt vmcnt(37)
	v_pk_fma_f32 v[0:1], v[102:103], v[24:25], v[0:1] op_sel_hi:[0,1,1]
	v_pk_fma_f32 v[2:3], v[102:103], v[40:41], v[2:3] op_sel_hi:[0,1,1]
	s_waitcnt vmcnt(36)
	v_pk_fma_f32 v[0:1], v[102:103], v[34:35], v[0:1] op_sel:[1,0,0]
	v_pk_fma_f32 v[2:3], v[102:103], v[50:51], v[2:3] op_sel:[1,0,0]
	s_waitcnt vmcnt(35)
	v_pk_fma_f32 v[0:1], v[104:105], v[26:27], v[0:1] op_sel_hi:[0,1,1]
	v_pk_fma_f32 v[2:3], v[104:105], v[42:43], v[2:3] op_sel_hi:[0,1,1]
	s_waitcnt vmcnt(34)
	v_pk_fma_f32 v[0:1], v[104:105], v[36:37], v[0:1] op_sel:[1,0,0]
	v_pk_fma_f32 v[2:3], v[104:105], v[52:53], v[2:3] op_sel:[1,0,0]
	s_waitcnt vmcnt(33)
	v_pk_fma_f32 v[0:1], v[106:107], v[28:29], v[0:1] op_sel_hi:[0,1,1]
	v_pk_fma_f32 v[2:3], v[106:107], v[44:45], v[2:3] op_sel_hi:[0,1,1]
	s_waitcnt vmcnt(32)
	v_pk_fma_f32 v[0:1], v[106:107], v[38:39], v[0:1] op_sel:[1,0,0]
	v_pk_fma_f32 v[2:3], v[106:107], v[54:55], v[2:3] op_sel:[1,0,0]
	ds_read_b128 v[24:27], v5 offset:384
	ds_read_b128 v[28:31], v5 offset:400
	ds_read_b128 v[32:35], v5 offset:4480
	ds_read_b128 v[36:39], v5 offset:4496
	ds_read_b128 v[40:43], v5 offset:8576
	ds_read_b128 v[44:47], v5 offset:8592
	ds_read_b128 v[48:51], v5 offset:12672
	ds_read_b128 v[52:55], v5 offset:12688
	s_waitcnt lgkmcnt(0)
	v_mov_b32_e32 v72, v24
	v_mov_b32_e32 v73, v32
	v_mov_b32_e32 v74, v40
	v_mov_b32_e32 v75, v48
	v_mov_b32_e32 v32, v25
	v_mov_b32_e32 v48, v41
	v_mov_b32_e32 v24, v26
	v_mov_b32_e32 v25, v34
	v_mov_b32_e32 v40, v42
	v_mov_b32_e32 v41, v50
	v_mov_b32_e32 v34, v27
	v_mov_b32_e32 v50, v43
	v_mov_b32_e32 v26, v28
	v_mov_b32_e32 v27, v36
	v_mov_b32_e32 v42, v44
	v_mov_b32_e32 v43, v52
	v_mov_b32_e32 v36, v29
	v_mov_b32_e32 v52, v45
	v_mov_b32_e32 v28, v30
	v_mov_b32_e32 v29, v38
	v_mov_b32_e32 v44, v46
	v_mov_b32_e32 v45, v54
	v_mov_b32_e32 v38, v31
	v_mov_b32_e32 v54, v47
	s_waitcnt vmcnt(31)
	v_pk_fma_f32 v[0:1], v[108:109], v[72:73], v[0:1] op_sel_hi:[0,1,1]
	v_pk_fma_f32 v[2:3], v[108:109], v[74:75], v[2:3] op_sel_hi:[0,1,1]
	s_waitcnt vmcnt(30)
	v_pk_fma_f32 v[0:1], v[108:109], v[32:33], v[0:1] op_sel:[1,0,0]
	v_pk_fma_f32 v[2:3], v[108:109], v[48:49], v[2:3] op_sel:[1,0,0]
	s_waitcnt vmcnt(29)
	v_pk_fma_f32 v[0:1], v[110:111], v[24:25], v[0:1] op_sel_hi:[0,1,1]
	v_pk_fma_f32 v[2:3], v[110:111], v[40:41], v[2:3] op_sel_hi:[0,1,1]
	s_waitcnt vmcnt(28)
	v_pk_fma_f32 v[0:1], v[110:111], v[34:35], v[0:1] op_sel:[1,0,0]
	v_pk_fma_f32 v[2:3], v[110:111], v[50:51], v[2:3] op_sel:[1,0,0]
	s_waitcnt vmcnt(27)
	v_pk_fma_f32 v[0:1], v[112:113], v[26:27], v[0:1] op_sel_hi:[0,1,1]
	v_pk_fma_f32 v[2:3], v[112:113], v[42:43], v[2:3] op_sel_hi:[0,1,1]
	s_waitcnt vmcnt(26)
	v_pk_fma_f32 v[0:1], v[112:113], v[36:37], v[0:1] op_sel:[1,0,0]
	v_pk_fma_f32 v[2:3], v[112:113], v[52:53], v[2:3] op_sel:[1,0,0]
	s_waitcnt vmcnt(25)
	v_pk_fma_f32 v[0:1], v[114:115], v[28:29], v[0:1] op_sel_hi:[0,1,1]
	v_pk_fma_f32 v[2:3], v[114:115], v[44:45], v[2:3] op_sel_hi:[0,1,1]
	s_waitcnt vmcnt(24)
	v_pk_fma_f32 v[0:1], v[114:115], v[38:39], v[0:1] op_sel:[1,0,0]
	v_pk_fma_f32 v[2:3], v[114:115], v[54:55], v[2:3] op_sel:[1,0,0]
	ds_read_b128 v[24:27], v5 offset:416
	ds_read_b128 v[28:31], v5 offset:432
	ds_read_b128 v[32:35], v5 offset:4512
	ds_read_b128 v[36:39], v5 offset:4528
	ds_read_b128 v[40:43], v5 offset:8608
	ds_read_b128 v[44:47], v5 offset:8624
	ds_read_b128 v[48:51], v5 offset:12704
	ds_read_b128 v[52:55], v5 offset:12720
	s_waitcnt lgkmcnt(0)
	v_mov_b32_e32 v72, v24
	v_mov_b32_e32 v73, v32
	v_mov_b32_e32 v74, v40
	v_mov_b32_e32 v75, v48
	v_mov_b32_e32 v32, v25
	v_mov_b32_e32 v48, v41
	v_mov_b32_e32 v24, v26
	v_mov_b32_e32 v25, v34
	v_mov_b32_e32 v40, v42
	v_mov_b32_e32 v41, v50
	v_mov_b32_e32 v34, v27
	v_mov_b32_e32 v50, v43
	v_mov_b32_e32 v26, v28
	v_mov_b32_e32 v27, v36
	v_mov_b32_e32 v42, v44
	v_mov_b32_e32 v43, v52
	v_mov_b32_e32 v36, v29
	v_mov_b32_e32 v52, v45
	v_mov_b32_e32 v28, v30
	v_mov_b32_e32 v29, v38
	v_mov_b32_e32 v44, v46
	v_mov_b32_e32 v45, v54
	v_mov_b32_e32 v38, v31
	v_mov_b32_e32 v54, v47
	s_waitcnt vmcnt(23)
	v_pk_fma_f32 v[0:1], v[116:117], v[72:73], v[0:1] op_sel_hi:[0,1,1]
	v_pk_fma_f32 v[2:3], v[116:117], v[74:75], v[2:3] op_sel_hi:[0,1,1]
	s_waitcnt vmcnt(22)
	v_pk_fma_f32 v[0:1], v[116:117], v[32:33], v[0:1] op_sel:[1,0,0]
	v_pk_fma_f32 v[2:3], v[116:117], v[48:49], v[2:3] op_sel:[1,0,0]
	s_waitcnt vmcnt(21)
	v_pk_fma_f32 v[0:1], v[118:119], v[24:25], v[0:1] op_sel_hi:[0,1,1]
	v_pk_fma_f32 v[2:3], v[118:119], v[40:41], v[2:3] op_sel_hi:[0,1,1]
	s_waitcnt vmcnt(20)
	v_pk_fma_f32 v[0:1], v[118:119], v[34:35], v[0:1] op_sel:[1,0,0]
	v_pk_fma_f32 v[2:3], v[118:119], v[50:51], v[2:3] op_sel:[1,0,0]
	s_waitcnt vmcnt(19)
	v_pk_fma_f32 v[0:1], v[120:121], v[26:27], v[0:1] op_sel_hi:[0,1,1]
	v_pk_fma_f32 v[2:3], v[120:121], v[42:43], v[2:3] op_sel_hi:[0,1,1]
	s_waitcnt vmcnt(18)
	v_pk_fma_f32 v[0:1], v[120:121], v[36:37], v[0:1] op_sel:[1,0,0]
	v_pk_fma_f32 v[2:3], v[120:121], v[52:53], v[2:3] op_sel:[1,0,0]
	s_waitcnt vmcnt(17)
	v_pk_fma_f32 v[0:1], v[122:123], v[28:29], v[0:1] op_sel_hi:[0,1,1]
	v_pk_fma_f32 v[2:3], v[122:123], v[44:45], v[2:3] op_sel_hi:[0,1,1]
	s_waitcnt vmcnt(16)
	v_pk_fma_f32 v[0:1], v[122:123], v[38:39], v[0:1] op_sel:[1,0,0]
	v_pk_fma_f32 v[2:3], v[122:123], v[54:55], v[2:3] op_sel:[1,0,0]
	ds_read_b128 v[24:27], v5 offset:448
	ds_read_b128 v[28:31], v5 offset:464
	ds_read_b128 v[32:35], v5 offset:4544
	ds_read_b128 v[36:39], v5 offset:4560
	ds_read_b128 v[40:43], v5 offset:8640
	ds_read_b128 v[44:47], v5 offset:8656
	ds_read_b128 v[48:51], v5 offset:12736
	ds_read_b128 v[52:55], v5 offset:12752
	s_waitcnt lgkmcnt(0)
	v_mov_b32_e32 v72, v24
	v_mov_b32_e32 v73, v32
	v_mov_b32_e32 v74, v40
	v_mov_b32_e32 v75, v48
	v_mov_b32_e32 v32, v25
	v_mov_b32_e32 v48, v41
	v_mov_b32_e32 v24, v26
	v_mov_b32_e32 v25, v34
	v_mov_b32_e32 v40, v42
	v_mov_b32_e32 v41, v50
	v_mov_b32_e32 v34, v27
	v_mov_b32_e32 v50, v43
	v_mov_b32_e32 v26, v28
	v_mov_b32_e32 v27, v36
	v_mov_b32_e32 v42, v44
	v_mov_b32_e32 v43, v52
	v_mov_b32_e32 v36, v29
	v_mov_b32_e32 v52, v45
	v_mov_b32_e32 v28, v30
	v_mov_b32_e32 v29, v38
	v_mov_b32_e32 v44, v46
	v_mov_b32_e32 v45, v54
	v_mov_b32_e32 v38, v31
	v_mov_b32_e32 v54, v47
	s_waitcnt vmcnt(15)
	v_pk_fma_f32 v[0:1], v[124:125], v[72:73], v[0:1] op_sel_hi:[0,1,1]
	v_pk_fma_f32 v[2:3], v[124:125], v[74:75], v[2:3] op_sel_hi:[0,1,1]
	s_waitcnt vmcnt(14)
	v_pk_fma_f32 v[0:1], v[124:125], v[32:33], v[0:1] op_sel:[1,0,0]
	v_pk_fma_f32 v[2:3], v[124:125], v[48:49], v[2:3] op_sel:[1,0,0]
	s_waitcnt vmcnt(13)
	v_pk_fma_f32 v[0:1], v[126:127], v[24:25], v[0:1] op_sel_hi:[0,1,1]
	v_pk_fma_f32 v[2:3], v[126:127], v[40:41], v[2:3] op_sel_hi:[0,1,1]
	s_waitcnt vmcnt(12)
	v_pk_fma_f32 v[0:1], v[126:127], v[34:35], v[0:1] op_sel:[1,0,0]
	v_pk_fma_f32 v[2:3], v[126:127], v[50:51], v[2:3] op_sel:[1,0,0]
	s_waitcnt vmcnt(11)
	v_pk_fma_f32 v[0:1], v[128:129], v[26:27], v[0:1] op_sel_hi:[0,1,1]
	v_pk_fma_f32 v[2:3], v[128:129], v[42:43], v[2:3] op_sel_hi:[0,1,1]
	s_waitcnt vmcnt(10)
	v_pk_fma_f32 v[0:1], v[128:129], v[36:37], v[0:1] op_sel:[1,0,0]
	v_pk_fma_f32 v[2:3], v[128:129], v[52:53], v[2:3] op_sel:[1,0,0]
	s_waitcnt vmcnt(9)
	v_pk_fma_f32 v[0:1], v[130:131], v[28:29], v[0:1] op_sel_hi:[0,1,1]
	v_pk_fma_f32 v[2:3], v[130:131], v[44:45], v[2:3] op_sel_hi:[0,1,1]
	s_waitcnt vmcnt(8)
	v_pk_fma_f32 v[0:1], v[130:131], v[38:39], v[0:1] op_sel:[1,0,0]
	v_pk_fma_f32 v[2:3], v[130:131], v[54:55], v[2:3] op_sel:[1,0,0]
	ds_read_b128 v[24:27], v5 offset:480
	ds_read_b128 v[28:31], v5 offset:496
	ds_read_b128 v[32:35], v5 offset:4576
	ds_read_b128 v[36:39], v5 offset:4592
	ds_read_b128 v[40:43], v5 offset:8672
	ds_read_b128 v[44:47], v5 offset:8688
	ds_read_b128 v[48:51], v5 offset:12768
	ds_read_b128 v[52:55], v5 offset:12784
	s_waitcnt lgkmcnt(0)
	v_mov_b32_e32 v72, v24
	v_mov_b32_e32 v73, v32
	v_mov_b32_e32 v74, v40
	v_mov_b32_e32 v75, v48
	v_mov_b32_e32 v32, v25
	v_mov_b32_e32 v48, v41
	v_mov_b32_e32 v24, v26
	v_mov_b32_e32 v25, v34
	v_mov_b32_e32 v40, v42
	v_mov_b32_e32 v41, v50
	v_mov_b32_e32 v34, v27
	v_mov_b32_e32 v50, v43
	v_mov_b32_e32 v26, v28
	v_mov_b32_e32 v27, v36
	v_mov_b32_e32 v42, v44
	v_mov_b32_e32 v43, v52
	v_mov_b32_e32 v36, v29
	v_mov_b32_e32 v52, v45
	v_mov_b32_e32 v28, v30
	v_mov_b32_e32 v29, v38
	v_mov_b32_e32 v44, v46
	v_mov_b32_e32 v45, v54
	v_mov_b32_e32 v38, v31
	v_mov_b32_e32 v54, v47
	s_waitcnt vmcnt(7)
	v_pk_fma_f32 v[0:1], v[132:133], v[72:73], v[0:1] op_sel_hi:[0,1,1]
	v_pk_fma_f32 v[2:3], v[132:133], v[74:75], v[2:3] op_sel_hi:[0,1,1]
	s_waitcnt vmcnt(6)
	v_pk_fma_f32 v[0:1], v[132:133], v[32:33], v[0:1] op_sel:[1,0,0]
	v_pk_fma_f32 v[2:3], v[132:133], v[48:49], v[2:3] op_sel:[1,0,0]
	s_waitcnt vmcnt(5)
	v_pk_fma_f32 v[0:1], v[134:135], v[24:25], v[0:1] op_sel_hi:[0,1,1]
	v_pk_fma_f32 v[2:3], v[134:135], v[40:41], v[2:3] op_sel_hi:[0,1,1]
	s_waitcnt vmcnt(4)
	v_pk_fma_f32 v[0:1], v[134:135], v[34:35], v[0:1] op_sel:[1,0,0]
	v_pk_fma_f32 v[2:3], v[134:135], v[50:51], v[2:3] op_sel:[1,0,0]
	s_waitcnt vmcnt(3)
	v_pk_fma_f32 v[0:1], v[136:137], v[26:27], v[0:1] op_sel_hi:[0,1,1]
	v_pk_fma_f32 v[2:3], v[136:137], v[42:43], v[2:3] op_sel_hi:[0,1,1]
	s_waitcnt vmcnt(2)
	v_pk_fma_f32 v[0:1], v[136:137], v[36:37], v[0:1] op_sel:[1,0,0]
	v_pk_fma_f32 v[2:3], v[136:137], v[52:53], v[2:3] op_sel:[1,0,0]
	s_waitcnt vmcnt(1)
	v_pk_fma_f32 v[0:1], v[138:139], v[28:29], v[0:1] op_sel_hi:[0,1,1]
	v_pk_fma_f32 v[2:3], v[138:139], v[44:45], v[2:3] op_sel_hi:[0,1,1]
	s_waitcnt vmcnt(0)
	v_pk_fma_f32 v[0:1], v[138:139], v[38:39], v[0:1] op_sel:[1,0,0]
	v_pk_fma_f32 v[2:3], v[138:139], v[54:55], v[2:3] op_sel:[1,0,0]
	ds_write_b128 v9, v[0:3] offset:16384
	s_waitcnt lgkmcnt(0)
	s_barrier
	s_and_saveexec_b64 s[28:29], vcc
	s_cbranch_execz .LBB0_238
	v_cndmask_b32_e64 v0, v23, v22, s[0:1]
	v_ashrrev_i32_e32 v1, 31, v0
	v_lshlrev_b64 v[0:1], 2, v[0:1]
	v_lshl_add_u64 v[2:3], v[14:15], 0, v[0:1]
	global_load_dword v20, v[2:3], off
	ds_read2st64_b32 v[2:3], v7 offset0:64 offset1:68
	ds_read2st64_b32 v[14:15], v7 offset0:72 offset1:76
	ds_read2st64_b32 v[16:17], v7 offset0:80 offset1:84
	ds_read2st64_b32 v[18:19], v7 offset0:88 offset1:92
	v_lshl_add_u64 v[12:13], s[30:31], 0, v[12:13]
	s_waitcnt lgkmcnt(3)
	v_add_f32_e32 v2, 0, v2
	v_add_f32_e32 v2, v2, v3
	s_waitcnt lgkmcnt(2)
	v_add_f32_e32 v2, v2, v14
	v_add_f32_e32 v2, v2, v15
	s_waitcnt lgkmcnt(1)
	v_add_f32_e32 v2, v2, v16
	v_add_f32_e32 v2, v2, v17
	v_mad_i64_i32 v[10:11], s[0:1], v10, v4, 0
	s_waitcnt lgkmcnt(0)
	v_add_f32_e32 v2, v2, v18
	v_lshl_add_u64 v[10:11], v[10:11], 2, v[12:13]
	v_add_f32_e32 v2, v2, v19
	v_lshl_add_u64 v[0:1], v[10:11], 0, v[0:1]
	s_waitcnt vmcnt(0)
	v_add_f32_e32 v2, v2, v20
	global_store_dword v[0:1], v2, off
	s_branch .LBB0_238
